# v21 + the three bf16-residual epilogues (FFN-down layers 0/1, layer-1 out-proj) de-serialised the same way: 4 steps of residual loads in flight, saddr addressing, dead fragment registers as buffers
# baseline (speedup 1.0000x reference)
; __device__ __forceinline__ unsigned cvt_pk_bf16(float lo, float hi) { f32x2 v = {lo, hi}; bf16x2v b = __builtin_convertvector(v, bf16x2v); return __builtin_bit_cast(unsigned, b); }
;     __device__ __forceinline__ void operator()(const f32x4 (&acc)[2][2][4][2], const Unit& u, int wr, int wc, int fr, int fq) const {
;         const int row0 = u.pm * BM + wr * 64 + fr; const int col0 = u.pn * BM + wc * 32 + 8 * fq;
; #pragma unroll
;         for (int ai = 0; ai < 2; ++ai)
; #pragma unroll
;             for (int m = 0; m < 4; ++m) { const size_t off = (size_t)(row0 + ai * HALF + m * 16) * ldc + col0;
; #pragma unroll
;                 for (int bj = 0; bj < 2; ++bj) { f32x4 r0, r1;
;                     if (RF32) { r0 = __builtin_nontemporal_load((const f32x4*)((const float*)res + off + bj * HALF)); r1 = __builtin_nontemporal_load((const f32x4*)((const float*)res + off + bj * HALF + 4)); }
;                     else { const u32x4 q = *(const u32x4*)((const bf16_t*)res + off + bj * HALF);
;                         r0 = (f32x4){__builtin_bit_cast(float, q.x << 16), __builtin_bit_cast(float, q.x & 0xffff0000u), __builtin_bit_cast(float, q.y << 16), __builtin_bit_cast(float, q.y & 0xffff0000u)};
;                         r1 = (f32x4){__builtin_bit_cast(float, q.z << 16), __builtin_bit_cast(float, q.z & 0xffff0000u), __builtin_bit_cast(float, q.w << 16), __builtin_bit_cast(float, q.w & 0xffff0000u)}; }
;                     const f32x4 v0 = r0 * alpha + acc[ai][bj][m][0], v1 = r1 * alpha + acc[ai][bj][m][1];
;                     u32x4 w; w.x = cvt_pk_bf16(v0[0], v0[1]); w.y = cvt_pk_bf16(v0[2], v0[3]); w.z = cvt_pk_bf16(v1[0], v1[1]); w.w = cvt_pk_bf16(v1[2], v1[3]);
;                     *(u32x4*)(out + off + bj * HALF) = w; }
;                 if (m & 1) asm volatile("" ::: "memory"); }
;     }
.LBB0_1101:
	v_lshl_add_u32 v150, s20, 8, v155
	v_lshl_or_b32 v148, s39, 8, v156
	v_ashrrev_i32_e32 v151, 31, v150
	v_ashrrev_i32_e32 v149, 31, v148
	v_lshlrev_b64 v[146:147], 10, v[150:151]
	v_lshl_add_u64 v[146:147], v[146:147], 0, v[148:149]
	v_lshlrev_b64 v[146:147], 1, v[146:147]
	s_mov_b64 s[24:25], 0x40000
	s_andn2_b64 vcc, exec, s[4:5]
	s_mov_b64 s[4:5], -1
	s_mov_b64 s[24:25], 0x48000
	s_mov_b64 s[24:25], 0x50000
	s_mov_b64 s[24:25], 0x58000
	s_add_u32 s98, s68, 0x0
	s_addc_u32 s99, s69, 0
	global_load_dwordx4 v[184:187], v146, s[98:99]
	global_load_dwordx4 v[188:191], v146, s[98:99] offset:256
	s_add_u32 s98, s68, 0x8000
	s_addc_u32 s99, s69, 0
	global_load_dwordx4 v[192:195], v146, s[98:99]
	global_load_dwordx4 v[208:211], v146, s[98:99] offset:256
	s_add_u32 s98, s68, 0x10000
	s_addc_u32 s99, s69, 0
	global_load_dwordx4 v[212:215], v146, s[98:99]
	global_load_dwordx4 v[216:219], v146, s[98:99] offset:256
	s_add_u32 s98, s68, 0x18000
	s_addc_u32 s99, s69, 0
	global_load_dwordx4 v[220:223], v146, s[98:99]
	global_load_dwordx4 v[224:227], v146, s[98:99] offset:256
	s_waitcnt vmcnt(6)
	v_lshlrev_b32_e32 v176, 16, v184
	v_and_b32_e32 v177, 0xffff0000, v184
	v_lshlrev_b32_e32 v184, 16, v185
	v_and_b32_e32 v185, 0xffff0000, v185
	v_lshlrev_b32_e32 v178, 16, v186
	v_and_b32_e32 v179, 0xffff0000, v186
	v_lshlrev_b32_e32 v186, 16, v187
	v_and_b32_e32 v187, 0xffff0000, v187
	v_lshlrev_b32_e32 v180, 16, v188
	v_and_b32_e32 v181, 0xffff0000, v188
	v_lshlrev_b32_e32 v188, 16, v189
	v_and_b32_e32 v189, 0xffff0000, v189
	v_lshlrev_b32_e32 v182, 16, v190
	v_and_b32_e32 v183, 0xffff0000, v190
	v_lshlrev_b32_e32 v190, 16, v191
	v_and_b32_e32 v191, 0xffff0000, v191
	v_pk_fma_f32 v[128:129], v[184:185], s[12:13], v[128:129] op_sel_hi:[1,0,1]
	v_pk_fma_f32 v[126:127], v[176:177], s[12:13], v[126:127] op_sel_hi:[1,0,1]
	v_pk_fma_f32 v[124:125], v[186:187], s[12:13], v[124:125] op_sel_hi:[1,0,1]
	v_pk_fma_f32 v[122:123], v[178:179], s[12:13], v[122:123] op_sel_hi:[1,0,1]
	v_pk_fma_f32 v[120:121], v[188:189], s[12:13], v[120:121] op_sel_hi:[1,0,1]
	v_pk_fma_f32 v[118:119], v[180:181], s[12:13], v[118:119] op_sel_hi:[1,0,1]
	v_pk_fma_f32 v[184:185], v[190:191], s[12:13], v[116:117] op_sel_hi:[1,0,1]
	v_pk_fma_f32 v[186:187], v[182:183], s[12:13], v[114:115] op_sel_hi:[1,0,1]
	v_cvt_pk_bf16_f32 v114, v126, v127
	v_cvt_pk_bf16_f32 v115, v128, v129
	v_cvt_pk_bf16_f32 v116, v122, v123
	v_cvt_pk_bf16_f32 v117, v124, v125
	v_cvt_pk_bf16_f32 v118, v118, v119
	v_cvt_pk_bf16_f32 v119, v120, v121
	v_cvt_pk_bf16_f32 v120, v186, v187
	v_cvt_pk_bf16_f32 v121, v184, v185
	s_add_u32 s100, s80, 0x0
	s_addc_u32 s101, s81, 0
	global_store_dwordx4 v146, v[114:117], s[100:101]
	global_store_dwordx4 v146, v[118:121], s[100:101] offset:256
	s_add_u32 s98, s68, 0x40000
	s_addc_u32 s99, s69, 0
	global_load_dwordx4 v[184:187], v146, s[98:99]
	global_load_dwordx4 v[188:191], v146, s[98:99] offset:256
	s_waitcnt vmcnt(8)
	v_lshlrev_b32_e32 v128, 16, v192
	v_and_b32_e32 v129, 0xffff0000, v192
	v_lshlrev_b32_e32 v192, 16, v193
	v_and_b32_e32 v193, 0xffff0000, v193
	v_lshlrev_b32_e32 v162, 16, v194
	v_and_b32_e32 v163, 0xffff0000, v194
	v_lshlrev_b32_e32 v194, 16, v195
	v_and_b32_e32 v195, 0xffff0000, v195
	v_lshlrev_b32_e32 v164, 16, v208
	v_and_b32_e32 v165, 0xffff0000, v208
	v_lshlrev_b32_e32 v208, 16, v209
	v_and_b32_e32 v209, 0xffff0000, v209
	v_lshlrev_b32_e32 v166, 16, v210
	v_and_b32_e32 v167, 0xffff0000, v210
	v_lshlrev_b32_e32 v210, 16, v211
	v_and_b32_e32 v211, 0xffff0000, v211
	v_pk_fma_f32 v[112:113], v[192:193], s[12:13], v[112:113] op_sel_hi:[1,0,1]
	v_pk_fma_f32 v[110:111], v[128:129], s[12:13], v[110:111] op_sel_hi:[1,0,1]
	v_pk_fma_f32 v[108:109], v[194:195], s[12:13], v[108:109] op_sel_hi:[1,0,1]
	v_pk_fma_f32 v[106:107], v[162:163], s[12:13], v[106:107] op_sel_hi:[1,0,1]
	v_pk_fma_f32 v[104:105], v[208:209], s[12:13], v[104:105] op_sel_hi:[1,0,1]
	v_pk_fma_f32 v[102:103], v[164:165], s[12:13], v[102:103] op_sel_hi:[1,0,1]
	v_pk_fma_f32 v[192:193], v[210:211], s[12:13], v[100:101] op_sel_hi:[1,0,1]
	v_pk_fma_f32 v[194:195], v[166:167], s[12:13], v[98:99] op_sel_hi:[1,0,1]
	v_cvt_pk_bf16_f32 v98, v110, v111
	v_cvt_pk_bf16_f32 v99, v112, v113
	v_cvt_pk_bf16_f32 v100, v106, v107
	v_cvt_pk_bf16_f32 v101, v108, v109
	v_cvt_pk_bf16_f32 v102, v102, v103
	v_cvt_pk_bf16_f32 v103, v104, v105
	v_cvt_pk_bf16_f32 v104, v194, v195
	v_cvt_pk_bf16_f32 v105, v192, v193
	s_add_u32 s100, s80, 0x8000
	s_addc_u32 s101, s81, 0
	global_store_dwordx4 v146, v[98:101], s[100:101]
	global_store_dwordx4 v146, v[102:105], s[100:101] offset:256
	s_add_u32 s98, s68, 0x48000
	s_addc_u32 s99, s69, 0
	global_load_dwordx4 v[192:195], v146, s[98:99]
	global_load_dwordx4 v[208:211], v146, s[98:99] offset:256
	s_waitcnt vmcnt(10)
; __device__ __forceinline__ unsigned cvt_pk_bf16(float lo, float hi) { f32x2 v = {lo, hi}; bf16x2v b = __builtin_convertvector(v, bf16x2v); return __builtin_bit_cast(unsigned, b); }
;     __device__ __forceinline__ void operator()(const f32x4 (&acc)[2][2][4][2], const Unit& u, int wr, int wc, int fr, int fq) const {
;         const int row0 = u.pm * BM + wr * 64 + fr; const int col0 = u.pn * BM + wc * 32 + 8 * fq;
; #pragma unroll
;         for (int ai = 0; ai < 2; ++ai)
; #pragma unroll
;             for (int m = 0; m < 4; ++m) { const size_t off = (size_t)(row0 + ai * HALF + m * 16) * ldc + col0;
; #pragma unroll
;                 for (int bj = 0; bj < 2; ++bj) { f32x4 r0, r1;
;                     if (RF32) { r0 = __builtin_nontemporal_load((const f32x4*)((const float*)res + off + bj * HALF)); r1 = __builtin_nontemporal_load((const f32x4*)((const float*)res + off + bj * HALF + 4)); }
;                     else { const u32x4 q = *(const u32x4*)((const bf16_t*)res + off + bj * HALF);
;                         r0 = (f32x4){__builtin_bit_cast(float, q.x << 16), __builtin_bit_cast(float, q.x & 0xffff0000u), __builtin_bit_cast(float, q.y << 16), __builtin_bit_cast(float, q.y & 0xffff0000u)};
;                         r1 = (f32x4){__builtin_bit_cast(float, q.z << 16), __builtin_bit_cast(float, q.z & 0xffff0000u), __builtin_bit_cast(float, q.w << 16), __builtin_bit_cast(float, q.w & 0xffff0000u)}; }
;                     const f32x4 v0 = r0 * alpha + acc[ai][bj][m][0], v1 = r1 * alpha + acc[ai][bj][m][1];
;                     u32x4 w; w.x = cvt_pk_bf16(v0[0], v0[1]); w.y = cvt_pk_bf16(v0[2], v0[3]); w.z = cvt_pk_bf16(v1[0], v1[1]); w.w = cvt_pk_bf16(v1[2], v1[3]);
;                     *(u32x4*)(out + off + bj * HALF) = w; }
;                 if (m & 1) asm volatile("" ::: "memory"); }
;     }
	v_lshlrev_b32_e32 v112, 16, v212
	v_and_b32_e32 v113, 0xffff0000, v212
	v_lshlrev_b32_e32 v212, 16, v213
	v_and_b32_e32 v213, 0xffff0000, v213
	v_lshlrev_b32_e32 v114, 16, v214
	v_and_b32_e32 v115, 0xffff0000, v214
	v_lshlrev_b32_e32 v214, 16, v215
	v_and_b32_e32 v215, 0xffff0000, v215
	v_lshlrev_b32_e32 v116, 16, v216
	v_and_b32_e32 v117, 0xffff0000, v216
	v_lshlrev_b32_e32 v216, 16, v217
	v_and_b32_e32 v217, 0xffff0000, v217
	v_lshlrev_b32_e32 v118, 16, v218
	v_and_b32_e32 v119, 0xffff0000, v218
	v_lshlrev_b32_e32 v218, 16, v219
	v_and_b32_e32 v219, 0xffff0000, v219
	v_pk_fma_f32 v[96:97], v[212:213], s[12:13], v[96:97] op_sel_hi:[1,0,1]
	v_pk_fma_f32 v[94:95], v[112:113], s[12:13], v[94:95] op_sel_hi:[1,0,1]
	v_pk_fma_f32 v[92:93], v[214:215], s[12:13], v[92:93] op_sel_hi:[1,0,1]
	v_pk_fma_f32 v[90:91], v[114:115], s[12:13], v[90:91] op_sel_hi:[1,0,1]
	v_pk_fma_f32 v[88:89], v[216:217], s[12:13], v[88:89] op_sel_hi:[1,0,1]
	v_pk_fma_f32 v[86:87], v[116:117], s[12:13], v[86:87] op_sel_hi:[1,0,1]
	v_pk_fma_f32 v[212:213], v[218:219], s[12:13], v[84:85] op_sel_hi:[1,0,1]
	v_pk_fma_f32 v[214:215], v[118:119], s[12:13], v[82:83] op_sel_hi:[1,0,1]
	v_cvt_pk_bf16_f32 v82, v94, v95
	v_cvt_pk_bf16_f32 v83, v96, v97
	v_cvt_pk_bf16_f32 v84, v90, v91
	v_cvt_pk_bf16_f32 v85, v92, v93
	v_cvt_pk_bf16_f32 v86, v86, v87
	v_cvt_pk_bf16_f32 v87, v88, v89
	v_cvt_pk_bf16_f32 v88, v214, v215
	v_cvt_pk_bf16_f32 v89, v212, v213
	s_add_u32 s100, s80, 0x10000
	s_addc_u32 s101, s81, 0
	global_store_dwordx4 v146, v[82:85], s[100:101]
	global_store_dwordx4 v146, v[86:89], s[100:101] offset:256
	s_add_u32 s98, s68, 0x50000
	s_addc_u32 s99, s69, 0
	global_load_dwordx4 v[212:215], v146, s[98:99]
	global_load_dwordx4 v[216:219], v146, s[98:99] offset:256
	s_waitcnt vmcnt(12)
	v_lshlrev_b32_e32 v96, 16, v220
	v_and_b32_e32 v97, 0xffff0000, v220
	v_lshlrev_b32_e32 v220, 16, v221
	v_and_b32_e32 v221, 0xffff0000, v221
	v_lshlrev_b32_e32 v98, 16, v222
	v_and_b32_e32 v99, 0xffff0000, v222
	v_lshlrev_b32_e32 v222, 16, v223
	v_and_b32_e32 v223, 0xffff0000, v223
	v_lshlrev_b32_e32 v100, 16, v224
	v_and_b32_e32 v101, 0xffff0000, v224
	v_lshlrev_b32_e32 v224, 16, v225
	v_and_b32_e32 v225, 0xffff0000, v225
	v_lshlrev_b32_e32 v102, 16, v226
	v_and_b32_e32 v103, 0xffff0000, v226
	v_lshlrev_b32_e32 v226, 16, v227
	v_and_b32_e32 v227, 0xffff0000, v227
	v_pk_fma_f32 v[80:81], v[220:221], s[12:13], v[80:81] op_sel_hi:[1,0,1]
	v_pk_fma_f32 v[78:79], v[96:97], s[12:13], v[78:79] op_sel_hi:[1,0,1]
	v_pk_fma_f32 v[76:77], v[222:223], s[12:13], v[76:77] op_sel_hi:[1,0,1]
	v_pk_fma_f32 v[74:75], v[98:99], s[12:13], v[74:75] op_sel_hi:[1,0,1]
	v_pk_fma_f32 v[72:73], v[224:225], s[12:13], v[72:73] op_sel_hi:[1,0,1]
	v_pk_fma_f32 v[70:71], v[100:101], s[12:13], v[70:71] op_sel_hi:[1,0,1]
	v_pk_fma_f32 v[220:221], v[226:227], s[12:13], v[68:69] op_sel_hi:[1,0,1]
	v_pk_fma_f32 v[222:223], v[102:103], s[12:13], v[66:67] op_sel_hi:[1,0,1]
	v_cvt_pk_bf16_f32 v66, v78, v79
	v_cvt_pk_bf16_f32 v67, v80, v81
	v_cvt_pk_bf16_f32 v68, v74, v75
	v_cvt_pk_bf16_f32 v69, v76, v77
	v_cvt_pk_bf16_f32 v70, v70, v71
	v_cvt_pk_bf16_f32 v71, v72, v73
	v_cvt_pk_bf16_f32 v72, v222, v223
	v_cvt_pk_bf16_f32 v73, v220, v221
	s_add_u32 s100, s80, 0x18000
	s_addc_u32 s101, s81, 0
	global_store_dwordx4 v146, v[66:69], s[100:101]
	global_store_dwordx4 v146, v[70:73], s[100:101] offset:256
	s_add_u32 s98, s68, 0x58000
	s_addc_u32 s99, s69, 0
	global_load_dwordx4 v[220:223], v146, s[98:99]
	global_load_dwordx4 v[224:227], v146, s[98:99] offset:256
	s_waitcnt vmcnt(12)
	v_lshlrev_b32_e32 v80, 16, v184
	v_and_b32_e32 v81, 0xffff0000, v184
	v_lshlrev_b32_e32 v184, 16, v185
	v_and_b32_e32 v185, 0xffff0000, v185
	v_lshlrev_b32_e32 v82, 16, v186
	v_and_b32_e32 v83, 0xffff0000, v186
	v_lshlrev_b32_e32 v186, 16, v187
	v_and_b32_e32 v187, 0xffff0000, v187
	v_lshlrev_b32_e32 v84, 16, v188
	v_and_b32_e32 v85, 0xffff0000, v188
	v_lshlrev_b32_e32 v188, 16, v189
	v_and_b32_e32 v189, 0xffff0000, v189
	v_lshlrev_b32_e32 v86, 16, v190
	v_and_b32_e32 v87, 0xffff0000, v190
	v_lshlrev_b32_e32 v190, 16, v191
	v_and_b32_e32 v191, 0xffff0000, v191
	v_pk_fma_f32 v[64:65], v[184:185], s[12:13], v[64:65] op_sel_hi:[1,0,1]
	v_pk_fma_f32 v[62:63], v[80:81], s[12:13], v[62:63] op_sel_hi:[1,0,1]
	v_pk_fma_f32 v[60:61], v[186:187], s[12:13], v[60:61] op_sel_hi:[1,0,1]
	v_pk_fma_f32 v[58:59], v[82:83], s[12:13], v[58:59] op_sel_hi:[1,0,1]
	v_pk_fma_f32 v[56:57], v[188:189], s[12:13], v[56:57] op_sel_hi:[1,0,1]
	v_pk_fma_f32 v[54:55], v[84:85], s[12:13], v[54:55] op_sel_hi:[1,0,1]
	v_pk_fma_f32 v[184:185], v[190:191], s[12:13], v[52:53] op_sel_hi:[1,0,1]
	v_pk_fma_f32 v[186:187], v[86:87], s[12:13], v[50:51] op_sel_hi:[1,0,1]
	v_cvt_pk_bf16_f32 v50, v62, v63
	v_cvt_pk_bf16_f32 v51, v64, v65
	v_cvt_pk_bf16_f32 v52, v58, v59
	v_cvt_pk_bf16_f32 v53, v60, v61
	v_cvt_pk_bf16_f32 v54, v54, v55
	v_cvt_pk_bf16_f32 v55, v56, v57
	v_cvt_pk_bf16_f32 v56, v186, v187
	v_cvt_pk_bf16_f32 v57, v184, v185
	s_add_u32 s100, s80, 0x40000
	s_addc_u32 s101, s81, 0
	global_store_dwordx4 v146, v[50:53], s[100:101]
	global_store_dwordx4 v146, v[54:57], s[100:101] offset:256
	s_waitcnt vmcnt(10)
; __device__ __forceinline__ unsigned cvt_pk_bf16(float lo, float hi) { f32x2 v = {lo, hi}; bf16x2v b = __builtin_convertvector(v, bf16x2v); return __builtin_bit_cast(unsigned, b); }
;     __device__ __forceinline__ void operator()(const f32x4 (&acc)[2][2][4][2], const Unit& u, int wr, int wc, int fr, int fq) const {
;         const int row0 = u.pm * BM + wr * 64 + fr; const int col0 = u.pn * BM + wc * 32 + 8 * fq;
; #pragma unroll
;         for (int ai = 0; ai < 2; ++ai)
; #pragma unroll
;             for (int m = 0; m < 4; ++m) { const size_t off = (size_t)(row0 + ai * HALF + m * 16) * ldc + col0;
; #pragma unroll
;                 for (int bj = 0; bj < 2; ++bj) { f32x4 r0, r1;
;                     if (RF32) { r0 = __builtin_nontemporal_load((const f32x4*)((const float*)res + off + bj * HALF)); r1 = __builtin_nontemporal_load((const f32x4*)((const float*)res + off + bj * HALF + 4)); }
;                     else { const u32x4 q = *(const u32x4*)((const bf16_t*)res + off + bj * HALF);
;                         r0 = (f32x4){__builtin_bit_cast(float, q.x << 16), __builtin_bit_cast(float, q.x & 0xffff0000u), __builtin_bit_cast(float, q.y << 16), __builtin_bit_cast(float, q.y & 0xffff0000u)};
;                         r1 = (f32x4){__builtin_bit_cast(float, q.z << 16), __builtin_bit_cast(float, q.z & 0xffff0000u), __builtin_bit_cast(float, q.w << 16), __builtin_bit_cast(float, q.w & 0xffff0000u)}; }
;                     const f32x4 v0 = r0 * alpha + acc[ai][bj][m][0], v1 = r1 * alpha + acc[ai][bj][m][1];
;                     u32x4 w; w.x = cvt_pk_bf16(v0[0], v0[1]); w.y = cvt_pk_bf16(v0[2], v0[3]); w.z = cvt_pk_bf16(v1[0], v1[1]); w.w = cvt_pk_bf16(v1[2], v1[3]);
;                     *(u32x4*)(out + off + bj * HALF) = w; }
;                 if (m & 1) asm volatile("" ::: "memory"); }
;     }
	v_lshlrev_b32_e32 v64, 16, v192
	v_and_b32_e32 v65, 0xffff0000, v192
	v_lshlrev_b32_e32 v192, 16, v193
	v_and_b32_e32 v193, 0xffff0000, v193
	v_lshlrev_b32_e32 v66, 16, v194
	v_and_b32_e32 v67, 0xffff0000, v194
	v_lshlrev_b32_e32 v194, 16, v195
	v_and_b32_e32 v195, 0xffff0000, v195
	v_lshlrev_b32_e32 v68, 16, v208
	v_and_b32_e32 v69, 0xffff0000, v208
	v_lshlrev_b32_e32 v208, 16, v209
	v_and_b32_e32 v209, 0xffff0000, v209
	v_lshlrev_b32_e32 v70, 16, v210
	v_and_b32_e32 v71, 0xffff0000, v210
	v_lshlrev_b32_e32 v210, 16, v211
	v_and_b32_e32 v211, 0xffff0000, v211
	v_pk_fma_f32 v[48:49], v[192:193], s[12:13], v[48:49] op_sel_hi:[1,0,1]
	v_pk_fma_f32 v[46:47], v[64:65], s[12:13], v[46:47] op_sel_hi:[1,0,1]
	v_pk_fma_f32 v[44:45], v[194:195], s[12:13], v[44:45] op_sel_hi:[1,0,1]
	v_pk_fma_f32 v[42:43], v[66:67], s[12:13], v[42:43] op_sel_hi:[1,0,1]
	v_pk_fma_f32 v[40:41], v[208:209], s[12:13], v[40:41] op_sel_hi:[1,0,1]
	v_pk_fma_f32 v[38:39], v[68:69], s[12:13], v[38:39] op_sel_hi:[1,0,1]
	v_pk_fma_f32 v[192:193], v[210:211], s[12:13], v[36:37] op_sel_hi:[1,0,1]
	v_pk_fma_f32 v[194:195], v[70:71], s[12:13], v[34:35] op_sel_hi:[1,0,1]
	v_cvt_pk_bf16_f32 v34, v46, v47
	v_cvt_pk_bf16_f32 v35, v48, v49
	v_cvt_pk_bf16_f32 v36, v42, v43
	v_cvt_pk_bf16_f32 v37, v44, v45
	v_cvt_pk_bf16_f32 v38, v38, v39
	v_cvt_pk_bf16_f32 v39, v40, v41
	v_cvt_pk_bf16_f32 v40, v194, v195
	v_cvt_pk_bf16_f32 v41, v192, v193
	s_add_u32 s100, s80, 0x48000
	s_addc_u32 s101, s81, 0
	global_store_dwordx4 v146, v[34:37], s[100:101]
	global_store_dwordx4 v146, v[38:41], s[100:101] offset:256
	s_waitcnt vmcnt(8)
	v_lshlrev_b32_e32 v48, 16, v212
	v_and_b32_e32 v49, 0xffff0000, v212
	v_lshlrev_b32_e32 v212, 16, v213
	v_and_b32_e32 v213, 0xffff0000, v213
	v_lshlrev_b32_e32 v50, 16, v214
	v_and_b32_e32 v51, 0xffff0000, v214
	v_lshlrev_b32_e32 v214, 16, v215
	v_and_b32_e32 v215, 0xffff0000, v215
	v_lshlrev_b32_e32 v52, 16, v216
	v_and_b32_e32 v53, 0xffff0000, v216
	v_lshlrev_b32_e32 v216, 16, v217
	v_and_b32_e32 v217, 0xffff0000, v217
	v_lshlrev_b32_e32 v54, 16, v218
	v_and_b32_e32 v55, 0xffff0000, v218
	v_lshlrev_b32_e32 v218, 16, v219
	v_and_b32_e32 v219, 0xffff0000, v219
	v_pk_fma_f32 v[32:33], v[212:213], s[12:13], v[32:33] op_sel_hi:[1,0,1]
	v_pk_fma_f32 v[30:31], v[48:49], s[12:13], v[30:31] op_sel_hi:[1,0,1]
	v_pk_fma_f32 v[28:29], v[214:215], s[12:13], v[28:29] op_sel_hi:[1,0,1]
	v_pk_fma_f32 v[26:27], v[50:51], s[12:13], v[26:27] op_sel_hi:[1,0,1]
	v_pk_fma_f32 v[24:25], v[216:217], s[12:13], v[24:25] op_sel_hi:[1,0,1]
	v_pk_fma_f32 v[22:23], v[52:53], s[12:13], v[22:23] op_sel_hi:[1,0,1]
	v_pk_fma_f32 v[212:213], v[218:219], s[12:13], v[20:21] op_sel_hi:[1,0,1]
	v_pk_fma_f32 v[214:215], v[54:55], s[12:13], v[18:19] op_sel_hi:[1,0,1]
	v_cvt_pk_bf16_f32 v18, v30, v31
	v_cvt_pk_bf16_f32 v19, v32, v33
	v_cvt_pk_bf16_f32 v20, v26, v27
	v_cvt_pk_bf16_f32 v21, v28, v29
	v_cvt_pk_bf16_f32 v22, v22, v23
	v_cvt_pk_bf16_f32 v23, v24, v25
	v_cvt_pk_bf16_f32 v24, v214, v215
	v_cvt_pk_bf16_f32 v25, v212, v213
	s_add_u32 s100, s80, 0x50000
	s_addc_u32 s101, s81, 0
	global_store_dwordx4 v146, v[18:21], s[100:101]
	global_store_dwordx4 v146, v[22:25], s[100:101] offset:256
	s_waitcnt vmcnt(6)
	v_lshlrev_b32_e32 v28, 16, v220
	v_and_b32_e32 v29, 0xffff0000, v220
	v_lshlrev_b32_e32 v220, 16, v221
	v_and_b32_e32 v221, 0xffff0000, v221
	v_lshlrev_b32_e32 v30, 16, v222
	v_and_b32_e32 v31, 0xffff0000, v222
	v_lshlrev_b32_e32 v222, 16, v223
	v_and_b32_e32 v223, 0xffff0000, v223
	v_lshlrev_b32_e32 v32, 16, v224
	v_and_b32_e32 v33, 0xffff0000, v224
	v_lshlrev_b32_e32 v224, 16, v225
	v_and_b32_e32 v225, 0xffff0000, v225
	v_lshlrev_b32_e32 v34, 16, v226
	v_and_b32_e32 v35, 0xffff0000, v226
	v_lshlrev_b32_e32 v226, 16, v227
	v_and_b32_e32 v227, 0xffff0000, v227
	v_pk_fma_f32 v[16:17], v[220:221], s[12:13], v[16:17] op_sel_hi:[1,0,1]
	v_pk_fma_f32 v[14:15], v[28:29], s[12:13], v[14:15] op_sel_hi:[1,0,1]
	v_pk_fma_f32 v[12:13], v[222:223], s[12:13], v[12:13] op_sel_hi:[1,0,1]
	v_pk_fma_f32 v[10:11], v[30:31], s[12:13], v[10:11] op_sel_hi:[1,0,1]
	v_pk_fma_f32 v[8:9], v[224:225], s[12:13], v[8:9] op_sel_hi:[1,0,1]
	v_pk_fma_f32 v[6:7], v[32:33], s[12:13], v[6:7] op_sel_hi:[1,0,1]
	v_pk_fma_f32 v[220:221], v[226:227], s[12:13], v[4:5] op_sel_hi:[1,0,1]
	v_pk_fma_f32 v[222:223], v[34:35], s[12:13], v[2:3] op_sel_hi:[1,0,1]
	v_cvt_pk_bf16_f32 v2, v14, v15
	v_cvt_pk_bf16_f32 v3, v16, v17
	v_cvt_pk_bf16_f32 v4, v10, v11
	v_cvt_pk_bf16_f32 v5, v12, v13
	v_cvt_pk_bf16_f32 v6, v6, v7
	v_cvt_pk_bf16_f32 v7, v8, v9
	v_cvt_pk_bf16_f32 v8, v222, v223
	v_cvt_pk_bf16_f32 v9, v220, v221
	s_add_u32 s100, s80, 0x58000
	s_addc_u32 s101, s81, 0
	global_store_dwordx4 v146, v[2:5], s[100:101]
	global_store_dwordx4 v146, v[6:9], s[100:101] offset:256
	s_cbranch_vccnz .LBB0_1090
	s_andn2_b64 vcc, exec, s[6:7]
	s_cbranch_vccnz .LBB0_1089
	s_barrier
	s_branch .LBB0_1089

; __device__ __forceinline__ unsigned cvt_pk_bf16(float lo, float hi) { f32x2 v = {lo, hi}; bf16x2v b = __builtin_convertvector(v, bf16x2v); return __builtin_bit_cast(unsigned, b); }
;     __device__ __forceinline__ void operator()(const f32x4 (&acc)[2][2][4][2], const Unit& u, int wr, int wc, int fr, int fq) const {
;         const int row0 = u.pm * BM + wr * 64 + fr; const int col0 = u.pn * BM + wc * 32 + 8 * fq;
; #pragma unroll
;         for (int ai = 0; ai < 2; ++ai)
; #pragma unroll
;             for (int m = 0; m < 4; ++m) { const size_t off = (size_t)(row0 + ai * HALF + m * 16) * ldc + col0;
; #pragma unroll
;                 for (int bj = 0; bj < 2; ++bj) { f32x4 r0, r1;
;                     if (RF32) { r0 = __builtin_nontemporal_load((const f32x4*)((const float*)res + off + bj * HALF)); r1 = __builtin_nontemporal_load((const f32x4*)((const float*)res + off + bj * HALF + 4)); }
;                     else { const u32x4 q = *(const u32x4*)((const bf16_t*)res + off + bj * HALF);
;                         r0 = (f32x4){__builtin_bit_cast(float, q.x << 16), __builtin_bit_cast(float, q.x & 0xffff0000u), __builtin_bit_cast(float, q.y << 16), __builtin_bit_cast(float, q.y & 0xffff0000u)};
;                         r1 = (f32x4){__builtin_bit_cast(float, q.z << 16), __builtin_bit_cast(float, q.z & 0xffff0000u), __builtin_bit_cast(float, q.w << 16), __builtin_bit_cast(float, q.w & 0xffff0000u)}; }
;                     const f32x4 v0 = r0 * alpha + acc[ai][bj][m][0], v1 = r1 * alpha + acc[ai][bj][m][1];
;                     u32x4 w; w.x = cvt_pk_bf16(v0[0], v0[1]); w.y = cvt_pk_bf16(v0[2], v0[3]); w.z = cvt_pk_bf16(v1[0], v1[1]); w.w = cvt_pk_bf16(v1[2], v1[3]);
;                     *(u32x4*)(out + off + bj * HALF) = w; }
;                 if (m & 1) asm volatile("" ::: "memory"); }
;     }
.LBB0_1451:
	v_lshl_add_u32 v148, s30, 8, v152
	v_lshl_or_b32 v146, s47, 8, v153
	v_ashrrev_i32_e32 v149, 31, v148
	v_ashrrev_i32_e32 v147, 31, v146
	v_lshlrev_b64 v[144:145], 10, v[148:149]
	v_lshl_add_u64 v[144:145], v[144:145], 0, v[146:147]
	v_lshlrev_b64 v[144:145], 1, v[144:145]
	s_andn2_b64 vcc, exec, s[4:5]
	s_mov_b64 s[4:5], -1
	s_add_u32 s98, s68, 0x0
	s_addc_u32 s99, s69, 0
	global_load_dwordx4 v[184:187], v144, s[98:99]
	global_load_dwordx4 v[188:191], v144, s[98:99] offset:256
	s_add_u32 s98, s68, 0x8000
	s_addc_u32 s99, s69, 0
	global_load_dwordx4 v[192:195], v144, s[98:99]
	global_load_dwordx4 v[208:211], v144, s[98:99] offset:256
	s_add_u32 s98, s68, 0x10000
	s_addc_u32 s99, s69, 0
	global_load_dwordx4 v[212:215], v144, s[98:99]
	global_load_dwordx4 v[216:219], v144, s[98:99] offset:256
	s_add_u32 s98, s68, 0x18000
	s_addc_u32 s99, s69, 0
	global_load_dwordx4 v[220:223], v144, s[98:99]
	global_load_dwordx4 v[224:227], v144, s[98:99] offset:256
	s_waitcnt vmcnt(6)
	v_lshlrev_b32_e32 v174, 16, v184
	v_and_b32_e32 v175, 0xffff0000, v184
	v_lshlrev_b32_e32 v184, 16, v185
	v_and_b32_e32 v185, 0xffff0000, v185
	v_lshlrev_b32_e32 v176, 16, v186
	v_and_b32_e32 v177, 0xffff0000, v186
	v_lshlrev_b32_e32 v186, 16, v187
	v_and_b32_e32 v187, 0xffff0000, v187
	v_lshlrev_b32_e32 v178, 16, v188
	v_and_b32_e32 v179, 0xffff0000, v188
	v_lshlrev_b32_e32 v188, 16, v189
	v_and_b32_e32 v189, 0xffff0000, v189
	v_lshlrev_b32_e32 v180, 16, v190
	v_and_b32_e32 v181, 0xffff0000, v190
	v_lshlrev_b32_e32 v190, 16, v191
	v_and_b32_e32 v191, 0xffff0000, v191
	v_pk_fma_f32 v[126:127], v[184:185], s[14:15], v[126:127] op_sel_hi:[1,0,1]
	v_pk_fma_f32 v[124:125], v[174:175], s[14:15], v[124:125] op_sel_hi:[1,0,1]
	v_pk_fma_f32 v[122:123], v[186:187], s[14:15], v[122:123] op_sel_hi:[1,0,1]
	v_pk_fma_f32 v[120:121], v[176:177], s[14:15], v[120:121] op_sel_hi:[1,0,1]
	v_pk_fma_f32 v[118:119], v[188:189], s[14:15], v[118:119] op_sel_hi:[1,0,1]
	v_pk_fma_f32 v[116:117], v[178:179], s[14:15], v[116:117] op_sel_hi:[1,0,1]
	v_pk_fma_f32 v[184:185], v[190:191], s[14:15], v[114:115] op_sel_hi:[1,0,1]
	v_pk_fma_f32 v[186:187], v[180:181], s[14:15], v[112:113] op_sel_hi:[1,0,1]
	v_cvt_pk_bf16_f32 v112, v124, v125
	v_cvt_pk_bf16_f32 v113, v126, v127
	v_cvt_pk_bf16_f32 v114, v120, v121
	v_cvt_pk_bf16_f32 v115, v122, v123
	v_cvt_pk_bf16_f32 v116, v116, v117
	v_cvt_pk_bf16_f32 v117, v118, v119
	v_cvt_pk_bf16_f32 v118, v186, v187
	v_cvt_pk_bf16_f32 v119, v184, v185
	s_add_u32 s100, s80, 0x0
	s_addc_u32 s101, s81, 0
	global_store_dwordx4 v144, v[112:115], s[100:101]
	global_store_dwordx4 v144, v[116:119], s[100:101] offset:256
	s_add_u32 s98, s68, 0x40000
	s_addc_u32 s99, s69, 0
	global_load_dwordx4 v[184:187], v144, s[98:99]
	global_load_dwordx4 v[188:191], v144, s[98:99] offset:256
	s_waitcnt vmcnt(8)
	v_lshlrev_b32_e32 v126, 16, v192
	v_and_b32_e32 v127, 0xffff0000, v192
	v_lshlrev_b32_e32 v192, 16, v193
	v_and_b32_e32 v193, 0xffff0000, v193
	v_lshlrev_b32_e32 v160, 16, v194
	v_and_b32_e32 v161, 0xffff0000, v194
	v_lshlrev_b32_e32 v194, 16, v195
	v_and_b32_e32 v195, 0xffff0000, v195
	v_lshlrev_b32_e32 v162, 16, v208
	v_and_b32_e32 v163, 0xffff0000, v208
	v_lshlrev_b32_e32 v208, 16, v209
	v_and_b32_e32 v209, 0xffff0000, v209
	v_lshlrev_b32_e32 v164, 16, v210
	v_and_b32_e32 v165, 0xffff0000, v210
	v_lshlrev_b32_e32 v210, 16, v211
	v_and_b32_e32 v211, 0xffff0000, v211
	v_pk_fma_f32 v[110:111], v[192:193], s[14:15], v[110:111] op_sel_hi:[1,0,1]
	v_pk_fma_f32 v[108:109], v[126:127], s[14:15], v[108:109] op_sel_hi:[1,0,1]
	v_pk_fma_f32 v[106:107], v[194:195], s[14:15], v[106:107] op_sel_hi:[1,0,1]
	v_pk_fma_f32 v[104:105], v[160:161], s[14:15], v[104:105] op_sel_hi:[1,0,1]
	v_pk_fma_f32 v[102:103], v[208:209], s[14:15], v[102:103] op_sel_hi:[1,0,1]
	v_pk_fma_f32 v[100:101], v[162:163], s[14:15], v[100:101] op_sel_hi:[1,0,1]
	v_pk_fma_f32 v[192:193], v[210:211], s[14:15], v[98:99] op_sel_hi:[1,0,1]
	v_pk_fma_f32 v[194:195], v[164:165], s[14:15], v[96:97] op_sel_hi:[1,0,1]
	v_cvt_pk_bf16_f32 v96, v108, v109
	v_cvt_pk_bf16_f32 v97, v110, v111
	v_cvt_pk_bf16_f32 v98, v104, v105
	v_cvt_pk_bf16_f32 v99, v106, v107
	v_cvt_pk_bf16_f32 v100, v100, v101
	v_cvt_pk_bf16_f32 v101, v102, v103
	v_cvt_pk_bf16_f32 v102, v194, v195
	v_cvt_pk_bf16_f32 v103, v192, v193
	s_add_u32 s100, s80, 0x8000
	s_addc_u32 s101, s81, 0
	global_store_dwordx4 v144, v[96:99], s[100:101]
	global_store_dwordx4 v144, v[100:103], s[100:101] offset:256
	s_add_u32 s98, s68, 0x48000
	s_addc_u32 s99, s69, 0
	global_load_dwordx4 v[192:195], v144, s[98:99]
	global_load_dwordx4 v[208:211], v144, s[98:99] offset:256
	s_waitcnt vmcnt(10)
	v_lshlrev_b32_e32 v110, 16, v212
	v_and_b32_e32 v111, 0xffff0000, v212
	v_lshlrev_b32_e32 v212, 16, v213
	v_and_b32_e32 v213, 0xffff0000, v213
	v_lshlrev_b32_e32 v112, 16, v214
	v_and_b32_e32 v113, 0xffff0000, v214
	v_lshlrev_b32_e32 v214, 16, v215
	v_and_b32_e32 v215, 0xffff0000, v215
	v_lshlrev_b32_e32 v114, 16, v216
	v_and_b32_e32 v115, 0xffff0000, v216
	v_lshlrev_b32_e32 v216, 16, v217
	v_and_b32_e32 v217, 0xffff0000, v217
	v_lshlrev_b32_e32 v116, 16, v218
	v_and_b32_e32 v117, 0xffff0000, v218
	v_lshlrev_b32_e32 v218, 16, v219
	v_and_b32_e32 v219, 0xffff0000, v219
	v_pk_fma_f32 v[94:95], v[212:213], s[14:15], v[94:95] op_sel_hi:[1,0,1]
	v_pk_fma_f32 v[92:93], v[110:111], s[14:15], v[92:93] op_sel_hi:[1,0,1]
	v_pk_fma_f32 v[90:91], v[214:215], s[14:15], v[90:91] op_sel_hi:[1,0,1]
	v_pk_fma_f32 v[88:89], v[112:113], s[14:15], v[88:89] op_sel_hi:[1,0,1]
	v_pk_fma_f32 v[86:87], v[216:217], s[14:15], v[86:87] op_sel_hi:[1,0,1]
	v_pk_fma_f32 v[84:85], v[114:115], s[14:15], v[84:85] op_sel_hi:[1,0,1]
	v_pk_fma_f32 v[212:213], v[218:219], s[14:15], v[82:83] op_sel_hi:[1,0,1]
	v_pk_fma_f32 v[214:215], v[116:117], s[14:15], v[80:81] op_sel_hi:[1,0,1]
	v_cvt_pk_bf16_f32 v80, v92, v93
	v_cvt_pk_bf16_f32 v81, v94, v95
	v_cvt_pk_bf16_f32 v82, v88, v89
	v_cvt_pk_bf16_f32 v83, v90, v91
	v_cvt_pk_bf16_f32 v84, v84, v85
	v_cvt_pk_bf16_f32 v85, v86, v87
	v_cvt_pk_bf16_f32 v86, v214, v215
	v_cvt_pk_bf16_f32 v87, v212, v213
	s_add_u32 s100, s80, 0x10000
	s_addc_u32 s101, s81, 0
	global_store_dwordx4 v144, v[80:83], s[100:101]
	global_store_dwordx4 v144, v[84:87], s[100:101] offset:256
	s_add_u32 s98, s68, 0x50000
	s_addc_u32 s99, s69, 0
	global_load_dwordx4 v[212:215], v144, s[98:99]
	global_load_dwordx4 v[216:219], v144, s[98:99] offset:256
	s_waitcnt vmcnt(12)
; __device__ __forceinline__ unsigned cvt_pk_bf16(float lo, float hi) { f32x2 v = {lo, hi}; bf16x2v b = __builtin_convertvector(v, bf16x2v); return __builtin_bit_cast(unsigned, b); }
;     __device__ __forceinline__ void operator()(const f32x4 (&acc)[2][2][4][2], const Unit& u, int wr, int wc, int fr, int fq) const {
;         const int row0 = u.pm * BM + wr * 64 + fr; const int col0 = u.pn * BM + wc * 32 + 8 * fq;
; #pragma unroll
;         for (int ai = 0; ai < 2; ++ai)
; #pragma unroll
;             for (int m = 0; m < 4; ++m) { const size_t off = (size_t)(row0 + ai * HALF + m * 16) * ldc + col0;
; #pragma unroll
;                 for (int bj = 0; bj < 2; ++bj) { f32x4 r0, r1;
;                     if (RF32) { r0 = __builtin_nontemporal_load((const f32x4*)((const float*)res + off + bj * HALF)); r1 = __builtin_nontemporal_load((const f32x4*)((const float*)res + off + bj * HALF + 4)); }
;                     else { const u32x4 q = *(const u32x4*)((const bf16_t*)res + off + bj * HALF);
;                         r0 = (f32x4){__builtin_bit_cast(float, q.x << 16), __builtin_bit_cast(float, q.x & 0xffff0000u), __builtin_bit_cast(float, q.y << 16), __builtin_bit_cast(float, q.y & 0xffff0000u)};
;                         r1 = (f32x4){__builtin_bit_cast(float, q.z << 16), __builtin_bit_cast(float, q.z & 0xffff0000u), __builtin_bit_cast(float, q.w << 16), __builtin_bit_cast(float, q.w & 0xffff0000u)}; }
;                     const f32x4 v0 = r0 * alpha + acc[ai][bj][m][0], v1 = r1 * alpha + acc[ai][bj][m][1];
;                     u32x4 w; w.x = cvt_pk_bf16(v0[0], v0[1]); w.y = cvt_pk_bf16(v0[2], v0[3]); w.z = cvt_pk_bf16(v1[0], v1[1]); w.w = cvt_pk_bf16(v1[2], v1[3]);
;                     *(u32x4*)(out + off + bj * HALF) = w; }
;                 if (m & 1) asm volatile("" ::: "memory"); }
;     }
	v_lshlrev_b32_e32 v94, 16, v220
	v_and_b32_e32 v95, 0xffff0000, v220
	v_lshlrev_b32_e32 v220, 16, v221
	v_and_b32_e32 v221, 0xffff0000, v221
	v_lshlrev_b32_e32 v96, 16, v222
	v_and_b32_e32 v97, 0xffff0000, v222
	v_lshlrev_b32_e32 v222, 16, v223
	v_and_b32_e32 v223, 0xffff0000, v223
	v_lshlrev_b32_e32 v98, 16, v224
	v_and_b32_e32 v99, 0xffff0000, v224
	v_lshlrev_b32_e32 v224, 16, v225
	v_and_b32_e32 v225, 0xffff0000, v225
	v_lshlrev_b32_e32 v100, 16, v226
	v_and_b32_e32 v101, 0xffff0000, v226
	v_lshlrev_b32_e32 v226, 16, v227
	v_and_b32_e32 v227, 0xffff0000, v227
	v_pk_fma_f32 v[78:79], v[220:221], s[14:15], v[78:79] op_sel_hi:[1,0,1]
	v_pk_fma_f32 v[76:77], v[94:95], s[14:15], v[76:77] op_sel_hi:[1,0,1]
	v_pk_fma_f32 v[74:75], v[222:223], s[14:15], v[74:75] op_sel_hi:[1,0,1]
	v_pk_fma_f32 v[72:73], v[96:97], s[14:15], v[72:73] op_sel_hi:[1,0,1]
	v_pk_fma_f32 v[70:71], v[224:225], s[14:15], v[70:71] op_sel_hi:[1,0,1]
	v_pk_fma_f32 v[68:69], v[98:99], s[14:15], v[68:69] op_sel_hi:[1,0,1]
	v_pk_fma_f32 v[220:221], v[226:227], s[14:15], v[66:67] op_sel_hi:[1,0,1]
	v_pk_fma_f32 v[222:223], v[100:101], s[14:15], v[64:65] op_sel_hi:[1,0,1]
	v_cvt_pk_bf16_f32 v64, v76, v77
	v_cvt_pk_bf16_f32 v65, v78, v79
	v_cvt_pk_bf16_f32 v66, v72, v73
	v_cvt_pk_bf16_f32 v67, v74, v75
	v_cvt_pk_bf16_f32 v68, v68, v69
	v_cvt_pk_bf16_f32 v69, v70, v71
	v_cvt_pk_bf16_f32 v70, v222, v223
	v_cvt_pk_bf16_f32 v71, v220, v221
	s_add_u32 s100, s80, 0x18000
	s_addc_u32 s101, s81, 0
	global_store_dwordx4 v144, v[64:67], s[100:101]
	global_store_dwordx4 v144, v[68:71], s[100:101] offset:256
	s_add_u32 s98, s68, 0x58000
	s_addc_u32 s99, s69, 0
	global_load_dwordx4 v[220:223], v144, s[98:99]
	global_load_dwordx4 v[224:227], v144, s[98:99] offset:256
	s_waitcnt vmcnt(12)
	v_lshlrev_b32_e32 v78, 16, v184
	v_and_b32_e32 v79, 0xffff0000, v184
	v_lshlrev_b32_e32 v184, 16, v185
	v_and_b32_e32 v185, 0xffff0000, v185
	v_lshlrev_b32_e32 v80, 16, v186
	v_and_b32_e32 v81, 0xffff0000, v186
	v_lshlrev_b32_e32 v186, 16, v187
	v_and_b32_e32 v187, 0xffff0000, v187
	v_lshlrev_b32_e32 v82, 16, v188
	v_and_b32_e32 v83, 0xffff0000, v188
	v_lshlrev_b32_e32 v188, 16, v189
	v_and_b32_e32 v189, 0xffff0000, v189
	v_lshlrev_b32_e32 v84, 16, v190
	v_and_b32_e32 v85, 0xffff0000, v190
	v_lshlrev_b32_e32 v190, 16, v191
	v_and_b32_e32 v191, 0xffff0000, v191
	v_pk_fma_f32 v[62:63], v[184:185], s[14:15], v[62:63] op_sel_hi:[1,0,1]
	v_pk_fma_f32 v[60:61], v[78:79], s[14:15], v[60:61] op_sel_hi:[1,0,1]
	v_pk_fma_f32 v[58:59], v[186:187], s[14:15], v[58:59] op_sel_hi:[1,0,1]
	v_pk_fma_f32 v[56:57], v[80:81], s[14:15], v[56:57] op_sel_hi:[1,0,1]
	v_pk_fma_f32 v[54:55], v[188:189], s[14:15], v[54:55] op_sel_hi:[1,0,1]
	v_pk_fma_f32 v[52:53], v[82:83], s[14:15], v[52:53] op_sel_hi:[1,0,1]
	v_pk_fma_f32 v[184:185], v[190:191], s[14:15], v[50:51] op_sel_hi:[1,0,1]
	v_pk_fma_f32 v[186:187], v[84:85], s[14:15], v[48:49] op_sel_hi:[1,0,1]
	v_cvt_pk_bf16_f32 v48, v60, v61
	v_cvt_pk_bf16_f32 v49, v62, v63
	v_cvt_pk_bf16_f32 v50, v56, v57
	v_cvt_pk_bf16_f32 v51, v58, v59
	v_cvt_pk_bf16_f32 v52, v52, v53
	v_cvt_pk_bf16_f32 v53, v54, v55
	v_cvt_pk_bf16_f32 v54, v186, v187
	v_cvt_pk_bf16_f32 v55, v184, v185
	s_add_u32 s100, s80, 0x40000
	s_addc_u32 s101, s81, 0
	global_store_dwordx4 v144, v[48:51], s[100:101]
	global_store_dwordx4 v144, v[52:55], s[100:101] offset:256
	s_waitcnt vmcnt(10)
; __device__ __forceinline__ unsigned cvt_pk_bf16(float lo, float hi) { f32x2 v = {lo, hi}; bf16x2v b = __builtin_convertvector(v, bf16x2v); return __builtin_bit_cast(unsigned, b); }
;     __device__ __forceinline__ void operator()(const f32x4 (&acc)[2][2][4][2], const Unit& u, int wr, int wc, int fr, int fq) const {
;         const int row0 = u.pm * BM + wr * 64 + fr; const int col0 = u.pn * BM + wc * 32 + 8 * fq;
; #pragma unroll
;         for (int ai = 0; ai < 2; ++ai)
; #pragma unroll
;             for (int m = 0; m < 4; ++m) { const size_t off = (size_t)(row0 + ai * HALF + m * 16) * ldc + col0;
; #pragma unroll
;                 for (int bj = 0; bj < 2; ++bj) { f32x4 r0, r1;
;                     if (RF32) { r0 = __builtin_nontemporal_load((const f32x4*)((const float*)res + off + bj * HALF)); r1 = __builtin_nontemporal_load((const f32x4*)((const float*)res + off + bj * HALF + 4)); }
;                     else { const u32x4 q = *(const u32x4*)((const bf16_t*)res + off + bj * HALF);
;                         r0 = (f32x4){__builtin_bit_cast(float, q.x << 16), __builtin_bit_cast(float, q.x & 0xffff0000u), __builtin_bit_cast(float, q.y << 16), __builtin_bit_cast(float, q.y & 0xffff0000u)};
;                         r1 = (f32x4){__builtin_bit_cast(float, q.z << 16), __builtin_bit_cast(float, q.z & 0xffff0000u), __builtin_bit_cast(float, q.w << 16), __builtin_bit_cast(float, q.w & 0xffff0000u)}; }
;                     const f32x4 v0 = r0 * alpha + acc[ai][bj][m][0], v1 = r1 * alpha + acc[ai][bj][m][1];
;                     u32x4 w; w.x = cvt_pk_bf16(v0[0], v0[1]); w.y = cvt_pk_bf16(v0[2], v0[3]); w.z = cvt_pk_bf16(v1[0], v1[1]); w.w = cvt_pk_bf16(v1[2], v1[3]);
;                     *(u32x4*)(out + off + bj * HALF) = w; }
;                 if (m & 1) asm volatile("" ::: "memory"); }
;     }
	v_lshlrev_b32_e32 v62, 16, v192
	v_and_b32_e32 v63, 0xffff0000, v192
	v_lshlrev_b32_e32 v192, 16, v193
	v_and_b32_e32 v193, 0xffff0000, v193
	v_lshlrev_b32_e32 v64, 16, v194
	v_and_b32_e32 v65, 0xffff0000, v194
	v_lshlrev_b32_e32 v194, 16, v195
	v_and_b32_e32 v195, 0xffff0000, v195
	v_lshlrev_b32_e32 v66, 16, v208
	v_and_b32_e32 v67, 0xffff0000, v208
	v_lshlrev_b32_e32 v208, 16, v209
	v_and_b32_e32 v209, 0xffff0000, v209
	v_lshlrev_b32_e32 v68, 16, v210
	v_and_b32_e32 v69, 0xffff0000, v210
	v_lshlrev_b32_e32 v210, 16, v211
	v_and_b32_e32 v211, 0xffff0000, v211
	v_pk_fma_f32 v[46:47], v[192:193], s[14:15], v[46:47] op_sel_hi:[1,0,1]
	v_pk_fma_f32 v[44:45], v[62:63], s[14:15], v[44:45] op_sel_hi:[1,0,1]
	v_pk_fma_f32 v[42:43], v[194:195], s[14:15], v[42:43] op_sel_hi:[1,0,1]
	v_pk_fma_f32 v[40:41], v[64:65], s[14:15], v[40:41] op_sel_hi:[1,0,1]
	v_pk_fma_f32 v[38:39], v[208:209], s[14:15], v[38:39] op_sel_hi:[1,0,1]
	v_pk_fma_f32 v[36:37], v[66:67], s[14:15], v[36:37] op_sel_hi:[1,0,1]
	v_pk_fma_f32 v[192:193], v[210:211], s[14:15], v[34:35] op_sel_hi:[1,0,1]
	v_pk_fma_f32 v[194:195], v[68:69], s[14:15], v[32:33] op_sel_hi:[1,0,1]
	v_cvt_pk_bf16_f32 v32, v44, v45
	v_cvt_pk_bf16_f32 v33, v46, v47
	v_cvt_pk_bf16_f32 v34, v40, v41
	v_cvt_pk_bf16_f32 v35, v42, v43
	v_cvt_pk_bf16_f32 v36, v36, v37
	v_cvt_pk_bf16_f32 v37, v38, v39
	v_cvt_pk_bf16_f32 v38, v194, v195
	v_cvt_pk_bf16_f32 v39, v192, v193
	s_add_u32 s100, s80, 0x48000
	s_addc_u32 s101, s81, 0
	global_store_dwordx4 v144, v[32:35], s[100:101]
	global_store_dwordx4 v144, v[36:39], s[100:101] offset:256
	s_waitcnt vmcnt(8)
	v_lshlrev_b32_e32 v46, 16, v212
	v_and_b32_e32 v47, 0xffff0000, v212
	v_lshlrev_b32_e32 v212, 16, v213
	v_and_b32_e32 v213, 0xffff0000, v213
	v_lshlrev_b32_e32 v48, 16, v214
	v_and_b32_e32 v49, 0xffff0000, v214
	v_lshlrev_b32_e32 v214, 16, v215
	v_and_b32_e32 v215, 0xffff0000, v215
	v_lshlrev_b32_e32 v50, 16, v216
	v_and_b32_e32 v51, 0xffff0000, v216
	v_lshlrev_b32_e32 v216, 16, v217
	v_and_b32_e32 v217, 0xffff0000, v217
	v_lshlrev_b32_e32 v52, 16, v218
	v_and_b32_e32 v53, 0xffff0000, v218
	v_lshlrev_b32_e32 v218, 16, v219
	v_and_b32_e32 v219, 0xffff0000, v219
	v_pk_fma_f32 v[30:31], v[212:213], s[14:15], v[30:31] op_sel_hi:[1,0,1]
	v_pk_fma_f32 v[28:29], v[46:47], s[14:15], v[28:29] op_sel_hi:[1,0,1]
	v_pk_fma_f32 v[26:27], v[214:215], s[14:15], v[26:27] op_sel_hi:[1,0,1]
	v_pk_fma_f32 v[24:25], v[48:49], s[14:15], v[24:25] op_sel_hi:[1,0,1]
	v_pk_fma_f32 v[22:23], v[216:217], s[14:15], v[22:23] op_sel_hi:[1,0,1]
	v_pk_fma_f32 v[20:21], v[50:51], s[14:15], v[20:21] op_sel_hi:[1,0,1]
	v_pk_fma_f32 v[212:213], v[218:219], s[14:15], v[18:19] op_sel_hi:[1,0,1]
	v_pk_fma_f32 v[214:215], v[52:53], s[14:15], v[16:17] op_sel_hi:[1,0,1]
	v_cvt_pk_bf16_f32 v16, v28, v29
	v_cvt_pk_bf16_f32 v17, v30, v31
	v_cvt_pk_bf16_f32 v18, v24, v25
	v_cvt_pk_bf16_f32 v19, v26, v27
	v_cvt_pk_bf16_f32 v20, v20, v21
	v_cvt_pk_bf16_f32 v21, v22, v23
	v_cvt_pk_bf16_f32 v22, v214, v215
	v_cvt_pk_bf16_f32 v23, v212, v213
	s_add_u32 s100, s80, 0x50000
	s_addc_u32 s101, s81, 0
	global_store_dwordx4 v144, v[16:19], s[100:101]
	global_store_dwordx4 v144, v[20:23], s[100:101] offset:256
	s_waitcnt vmcnt(6)
	v_lshlrev_b32_e32 v26, 16, v220
	v_and_b32_e32 v27, 0xffff0000, v220
	v_lshlrev_b32_e32 v220, 16, v221
	v_and_b32_e32 v221, 0xffff0000, v221
	v_lshlrev_b32_e32 v28, 16, v222
	v_and_b32_e32 v29, 0xffff0000, v222
	v_lshlrev_b32_e32 v222, 16, v223
	v_and_b32_e32 v223, 0xffff0000, v223
	v_lshlrev_b32_e32 v30, 16, v224
	v_and_b32_e32 v31, 0xffff0000, v224
	v_lshlrev_b32_e32 v224, 16, v225
	v_and_b32_e32 v225, 0xffff0000, v225
	v_lshlrev_b32_e32 v32, 16, v226
	v_and_b32_e32 v33, 0xffff0000, v226
	v_lshlrev_b32_e32 v226, 16, v227
	v_and_b32_e32 v227, 0xffff0000, v227
	v_pk_fma_f32 v[14:15], v[220:221], s[14:15], v[14:15] op_sel_hi:[1,0,1]
	v_pk_fma_f32 v[12:13], v[26:27], s[14:15], v[12:13] op_sel_hi:[1,0,1]
	v_pk_fma_f32 v[10:11], v[222:223], s[14:15], v[10:11] op_sel_hi:[1,0,1]
	v_pk_fma_f32 v[8:9], v[28:29], s[14:15], v[8:9] op_sel_hi:[1,0,1]
	v_pk_fma_f32 v[6:7], v[224:225], s[14:15], v[6:7] op_sel_hi:[1,0,1]
	v_pk_fma_f32 v[4:5], v[30:31], s[14:15], v[4:5] op_sel_hi:[1,0,1]
	v_pk_fma_f32 v[220:221], v[226:227], s[14:15], v[2:3] op_sel_hi:[1,0,1]
	v_pk_fma_f32 v[222:223], v[32:33], s[14:15], v[0:1] op_sel_hi:[1,0,1]
	v_cvt_pk_bf16_f32 v0, v12, v13
	v_cvt_pk_bf16_f32 v1, v14, v15
	v_cvt_pk_bf16_f32 v2, v8, v9
	v_cvt_pk_bf16_f32 v3, v10, v11
	v_cvt_pk_bf16_f32 v4, v4, v5
	v_cvt_pk_bf16_f32 v5, v6, v7
	v_cvt_pk_bf16_f32 v6, v222, v223
	v_cvt_pk_bf16_f32 v7, v220, v221
	s_add_u32 s100, s80, 0x58000
	s_addc_u32 s101, s81, 0
	global_store_dwordx4 v144, v[0:3], s[100:101]
	global_store_dwordx4 v144, v[4:7], s[100:101] offset:256
	s_cbranch_vccnz .LBB0_1440
	s_andn2_b64 vcc, exec, s[8:9]
	s_cbranch_vccnz .LBB0_1439
	s_barrier
	s_branch .LBB0_1439

; __device__ __forceinline__ unsigned cvt_pk_bf16(float lo, float hi) { f32x2 v = {lo, hi}; bf16x2v b = __builtin_convertvector(v, bf16x2v); return __builtin_bit_cast(unsigned, b); }
;     __device__ __forceinline__ void operator()(const f32x4 (&acc)[2][2][4][2], const Unit& u, int wr, int wc, int fr, int fq) const {
;         const int row0 = u.pm * BM + wr * 64 + fr; const int col0 = u.pn * BM + wc * 32 + 8 * fq;
; #pragma unroll
;         for (int ai = 0; ai < 2; ++ai)
; #pragma unroll
;             for (int m = 0; m < 4; ++m) { const size_t off = (size_t)(row0 + ai * HALF + m * 16) * ldc + col0;
; #pragma unroll
;                 for (int bj = 0; bj < 2; ++bj) { f32x4 r0, r1;
;                     if (RF32) { r0 = __builtin_nontemporal_load((const f32x4*)((const float*)res + off + bj * HALF)); r1 = __builtin_nontemporal_load((const f32x4*)((const float*)res + off + bj * HALF + 4)); }
;                     else { const u32x4 q = *(const u32x4*)((const bf16_t*)res + off + bj * HALF);
;                         r0 = (f32x4){__builtin_bit_cast(float, q.x << 16), __builtin_bit_cast(float, q.x & 0xffff0000u), __builtin_bit_cast(float, q.y << 16), __builtin_bit_cast(float, q.y & 0xffff0000u)};
;                         r1 = (f32x4){__builtin_bit_cast(float, q.z << 16), __builtin_bit_cast(float, q.z & 0xffff0000u), __builtin_bit_cast(float, q.w << 16), __builtin_bit_cast(float, q.w & 0xffff0000u)}; }
;                     const f32x4 v0 = r0 * alpha + acc[ai][bj][m][0], v1 = r1 * alpha + acc[ai][bj][m][1];
;                     u32x4 w; w.x = cvt_pk_bf16(v0[0], v0[1]); w.y = cvt_pk_bf16(v0[2], v0[3]); w.z = cvt_pk_bf16(v1[0], v1[1]); w.w = cvt_pk_bf16(v1[2], v1[3]);
;                     *(u32x4*)(out + off + bj * HALF) = w; }
;                 if (m & 1) asm volatile("" ::: "memory"); }
;     }
.LBB0_1706:
	v_lshl_add_u32 v148, s30, 8, v154
	v_lshl_or_b32 v146, s49, 8, v155
	v_ashrrev_i32_e32 v149, 31, v148
	v_ashrrev_i32_e32 v147, 31, v146
	v_lshlrev_b64 v[144:145], 10, v[148:149]
	v_lshl_add_u64 v[144:145], v[144:145], 0, v[146:147]
	v_lshlrev_b64 v[144:145], 1, v[144:145]
	s_andn2_b64 vcc, exec, s[4:5]
	s_mov_b64 s[4:5], -1
	s_add_u32 s98, s68, 0x0
	s_addc_u32 s99, s69, 0
	global_load_dwordx4 v[184:187], v144, s[98:99]
	global_load_dwordx4 v[188:191], v144, s[98:99] offset:256
	s_add_u32 s98, s68, 0x8000
	s_addc_u32 s99, s69, 0
	global_load_dwordx4 v[192:195], v144, s[98:99]
	global_load_dwordx4 v[208:211], v144, s[98:99] offset:256
	s_add_u32 s98, s68, 0x10000
	s_addc_u32 s99, s69, 0
	global_load_dwordx4 v[212:215], v144, s[98:99]
	global_load_dwordx4 v[216:219], v144, s[98:99] offset:256
	s_add_u32 s98, s68, 0x18000
	s_addc_u32 s99, s69, 0
	global_load_dwordx4 v[220:223], v144, s[98:99]
	global_load_dwordx4 v[224:227], v144, s[98:99] offset:256
	s_waitcnt vmcnt(6)
	v_lshlrev_b32_e32 v176, 16, v184
	v_and_b32_e32 v177, 0xffff0000, v184
	v_lshlrev_b32_e32 v184, 16, v185
	v_and_b32_e32 v185, 0xffff0000, v185
	v_lshlrev_b32_e32 v178, 16, v186
	v_and_b32_e32 v179, 0xffff0000, v186
	v_lshlrev_b32_e32 v186, 16, v187
	v_and_b32_e32 v187, 0xffff0000, v187
	v_lshlrev_b32_e32 v180, 16, v188
	v_and_b32_e32 v181, 0xffff0000, v188
	v_lshlrev_b32_e32 v188, 16, v189
	v_and_b32_e32 v189, 0xffff0000, v189
	v_lshlrev_b32_e32 v182, 16, v190
	v_and_b32_e32 v183, 0xffff0000, v190
	v_lshlrev_b32_e32 v190, 16, v191
	v_and_b32_e32 v191, 0xffff0000, v191
	v_pk_fma_f32 v[126:127], v[184:185], s[12:13], v[126:127] op_sel_hi:[1,0,1]
	v_pk_fma_f32 v[124:125], v[176:177], s[12:13], v[124:125] op_sel_hi:[1,0,1]
	v_pk_fma_f32 v[122:123], v[186:187], s[12:13], v[122:123] op_sel_hi:[1,0,1]
	v_pk_fma_f32 v[120:121], v[178:179], s[12:13], v[120:121] op_sel_hi:[1,0,1]
	v_pk_fma_f32 v[118:119], v[188:189], s[12:13], v[118:119] op_sel_hi:[1,0,1]
	v_pk_fma_f32 v[116:117], v[180:181], s[12:13], v[116:117] op_sel_hi:[1,0,1]
	v_pk_fma_f32 v[184:185], v[190:191], s[12:13], v[114:115] op_sel_hi:[1,0,1]
	v_pk_fma_f32 v[186:187], v[182:183], s[12:13], v[112:113] op_sel_hi:[1,0,1]
	v_cvt_pk_bf16_f32 v112, v124, v125
	v_cvt_pk_bf16_f32 v113, v126, v127
	v_cvt_pk_bf16_f32 v114, v120, v121
	v_cvt_pk_bf16_f32 v115, v122, v123
	v_cvt_pk_bf16_f32 v116, v116, v117
	v_cvt_pk_bf16_f32 v117, v118, v119
	v_cvt_pk_bf16_f32 v118, v186, v187
	v_cvt_pk_bf16_f32 v119, v184, v185
	s_add_u32 s100, s80, 0x0
	s_addc_u32 s101, s81, 0
	global_store_dwordx4 v144, v[112:115], s[100:101]
	global_store_dwordx4 v144, v[116:119], s[100:101] offset:256
	s_add_u32 s98, s68, 0x40000
	s_addc_u32 s99, s69, 0
	global_load_dwordx4 v[184:187], v144, s[98:99]
	global_load_dwordx4 v[188:191], v144, s[98:99] offset:256
	s_waitcnt vmcnt(8)
	v_lshlrev_b32_e32 v126, 16, v192
	v_and_b32_e32 v127, 0xffff0000, v192
	v_lshlrev_b32_e32 v192, 16, v193
	v_and_b32_e32 v193, 0xffff0000, v193
	v_lshlrev_b32_e32 v162, 16, v194
	v_and_b32_e32 v163, 0xffff0000, v194
	v_lshlrev_b32_e32 v194, 16, v195
	v_and_b32_e32 v195, 0xffff0000, v195
	v_lshlrev_b32_e32 v164, 16, v208
	v_and_b32_e32 v165, 0xffff0000, v208
	v_lshlrev_b32_e32 v208, 16, v209
	v_and_b32_e32 v209, 0xffff0000, v209
	v_lshlrev_b32_e32 v166, 16, v210
	v_and_b32_e32 v167, 0xffff0000, v210
	v_lshlrev_b32_e32 v210, 16, v211
	v_and_b32_e32 v211, 0xffff0000, v211
	v_pk_fma_f32 v[110:111], v[192:193], s[12:13], v[110:111] op_sel_hi:[1,0,1]
	v_pk_fma_f32 v[108:109], v[126:127], s[12:13], v[108:109] op_sel_hi:[1,0,1]
	v_pk_fma_f32 v[106:107], v[194:195], s[12:13], v[106:107] op_sel_hi:[1,0,1]
	v_pk_fma_f32 v[104:105], v[162:163], s[12:13], v[104:105] op_sel_hi:[1,0,1]
	v_pk_fma_f32 v[102:103], v[208:209], s[12:13], v[102:103] op_sel_hi:[1,0,1]
	v_pk_fma_f32 v[100:101], v[164:165], s[12:13], v[100:101] op_sel_hi:[1,0,1]
	v_pk_fma_f32 v[192:193], v[210:211], s[12:13], v[98:99] op_sel_hi:[1,0,1]
	v_pk_fma_f32 v[194:195], v[166:167], s[12:13], v[96:97] op_sel_hi:[1,0,1]
	v_cvt_pk_bf16_f32 v96, v108, v109
	v_cvt_pk_bf16_f32 v97, v110, v111
	v_cvt_pk_bf16_f32 v98, v104, v105
	v_cvt_pk_bf16_f32 v99, v106, v107
	v_cvt_pk_bf16_f32 v100, v100, v101
	v_cvt_pk_bf16_f32 v101, v102, v103
	v_cvt_pk_bf16_f32 v102, v194, v195
	v_cvt_pk_bf16_f32 v103, v192, v193
	s_add_u32 s100, s80, 0x8000
	s_addc_u32 s101, s81, 0
	global_store_dwordx4 v144, v[96:99], s[100:101]
	global_store_dwordx4 v144, v[100:103], s[100:101] offset:256
	s_add_u32 s98, s68, 0x48000
	s_addc_u32 s99, s69, 0
	global_load_dwordx4 v[192:195], v144, s[98:99]
	global_load_dwordx4 v[208:211], v144, s[98:99] offset:256
	s_waitcnt vmcnt(10)
	v_lshlrev_b32_e32 v110, 16, v212
	v_and_b32_e32 v111, 0xffff0000, v212
	v_lshlrev_b32_e32 v212, 16, v213
	v_and_b32_e32 v213, 0xffff0000, v213
	v_lshlrev_b32_e32 v112, 16, v214
	v_and_b32_e32 v113, 0xffff0000, v214
	v_lshlrev_b32_e32 v214, 16, v215
	v_and_b32_e32 v215, 0xffff0000, v215
	v_lshlrev_b32_e32 v114, 16, v216
	v_and_b32_e32 v115, 0xffff0000, v216
	v_lshlrev_b32_e32 v216, 16, v217
	v_and_b32_e32 v217, 0xffff0000, v217
	v_lshlrev_b32_e32 v116, 16, v218
	v_and_b32_e32 v117, 0xffff0000, v218
	v_lshlrev_b32_e32 v218, 16, v219
	v_and_b32_e32 v219, 0xffff0000, v219
	v_pk_fma_f32 v[94:95], v[212:213], s[12:13], v[94:95] op_sel_hi:[1,0,1]
	v_pk_fma_f32 v[92:93], v[110:111], s[12:13], v[92:93] op_sel_hi:[1,0,1]
	v_pk_fma_f32 v[90:91], v[214:215], s[12:13], v[90:91] op_sel_hi:[1,0,1]
	v_pk_fma_f32 v[88:89], v[112:113], s[12:13], v[88:89] op_sel_hi:[1,0,1]
	v_pk_fma_f32 v[86:87], v[216:217], s[12:13], v[86:87] op_sel_hi:[1,0,1]
	v_pk_fma_f32 v[84:85], v[114:115], s[12:13], v[84:85] op_sel_hi:[1,0,1]
	v_pk_fma_f32 v[212:213], v[218:219], s[12:13], v[82:83] op_sel_hi:[1,0,1]
	v_pk_fma_f32 v[214:215], v[116:117], s[12:13], v[80:81] op_sel_hi:[1,0,1]
	v_cvt_pk_bf16_f32 v80, v92, v93
	v_cvt_pk_bf16_f32 v81, v94, v95
	v_cvt_pk_bf16_f32 v82, v88, v89
	v_cvt_pk_bf16_f32 v83, v90, v91
	v_cvt_pk_bf16_f32 v84, v84, v85
	v_cvt_pk_bf16_f32 v85, v86, v87
	v_cvt_pk_bf16_f32 v86, v214, v215
	v_cvt_pk_bf16_f32 v87, v212, v213
	s_add_u32 s100, s80, 0x10000
	s_addc_u32 s101, s81, 0
	global_store_dwordx4 v144, v[80:83], s[100:101]
	global_store_dwordx4 v144, v[84:87], s[100:101] offset:256
	s_add_u32 s98, s68, 0x50000
	s_addc_u32 s99, s69, 0
	global_load_dwordx4 v[212:215], v144, s[98:99]
	global_load_dwordx4 v[216:219], v144, s[98:99] offset:256
	s_waitcnt vmcnt(12)
; __device__ __forceinline__ unsigned cvt_pk_bf16(float lo, float hi) { f32x2 v = {lo, hi}; bf16x2v b = __builtin_convertvector(v, bf16x2v); return __builtin_bit_cast(unsigned, b); }
;     __device__ __forceinline__ void operator()(const f32x4 (&acc)[2][2][4][2], const Unit& u, int wr, int wc, int fr, int fq) const {
;         const int row0 = u.pm * BM + wr * 64 + fr; const int col0 = u.pn * BM + wc * 32 + 8 * fq;
; #pragma unroll
;         for (int ai = 0; ai < 2; ++ai)
; #pragma unroll
;             for (int m = 0; m < 4; ++m) { const size_t off = (size_t)(row0 + ai * HALF + m * 16) * ldc + col0;
; #pragma unroll
;                 for (int bj = 0; bj < 2; ++bj) { f32x4 r0, r1;
;                     if (RF32) { r0 = __builtin_nontemporal_load((const f32x4*)((const float*)res + off + bj * HALF)); r1 = __builtin_nontemporal_load((const f32x4*)((const float*)res + off + bj * HALF + 4)); }
;                     else { const u32x4 q = *(const u32x4*)((const bf16_t*)res + off + bj * HALF);
;                         r0 = (f32x4){__builtin_bit_cast(float, q.x << 16), __builtin_bit_cast(float, q.x & 0xffff0000u), __builtin_bit_cast(float, q.y << 16), __builtin_bit_cast(float, q.y & 0xffff0000u)};
;                         r1 = (f32x4){__builtin_bit_cast(float, q.z << 16), __builtin_bit_cast(float, q.z & 0xffff0000u), __builtin_bit_cast(float, q.w << 16), __builtin_bit_cast(float, q.w & 0xffff0000u)}; }
;                     const f32x4 v0 = r0 * alpha + acc[ai][bj][m][0], v1 = r1 * alpha + acc[ai][bj][m][1];
;                     u32x4 w; w.x = cvt_pk_bf16(v0[0], v0[1]); w.y = cvt_pk_bf16(v0[2], v0[3]); w.z = cvt_pk_bf16(v1[0], v1[1]); w.w = cvt_pk_bf16(v1[2], v1[3]);
;                     *(u32x4*)(out + off + bj * HALF) = w; }
;                 if (m & 1) asm volatile("" ::: "memory"); }
;     }
	v_lshlrev_b32_e32 v94, 16, v220
	v_and_b32_e32 v95, 0xffff0000, v220
	v_lshlrev_b32_e32 v220, 16, v221
	v_and_b32_e32 v221, 0xffff0000, v221
	v_lshlrev_b32_e32 v96, 16, v222
	v_and_b32_e32 v97, 0xffff0000, v222
	v_lshlrev_b32_e32 v222, 16, v223
	v_and_b32_e32 v223, 0xffff0000, v223
	v_lshlrev_b32_e32 v98, 16, v224
	v_and_b32_e32 v99, 0xffff0000, v224
	v_lshlrev_b32_e32 v224, 16, v225
	v_and_b32_e32 v225, 0xffff0000, v225
	v_lshlrev_b32_e32 v100, 16, v226
	v_and_b32_e32 v101, 0xffff0000, v226
	v_lshlrev_b32_e32 v226, 16, v227
	v_and_b32_e32 v227, 0xffff0000, v227
	v_pk_fma_f32 v[78:79], v[220:221], s[12:13], v[78:79] op_sel_hi:[1,0,1]
	v_pk_fma_f32 v[76:77], v[94:95], s[12:13], v[76:77] op_sel_hi:[1,0,1]
	v_pk_fma_f32 v[74:75], v[222:223], s[12:13], v[74:75] op_sel_hi:[1,0,1]
	v_pk_fma_f32 v[72:73], v[96:97], s[12:13], v[72:73] op_sel_hi:[1,0,1]
	v_pk_fma_f32 v[70:71], v[224:225], s[12:13], v[70:71] op_sel_hi:[1,0,1]
	v_pk_fma_f32 v[68:69], v[98:99], s[12:13], v[68:69] op_sel_hi:[1,0,1]
	v_pk_fma_f32 v[220:221], v[226:227], s[12:13], v[66:67] op_sel_hi:[1,0,1]
	v_pk_fma_f32 v[222:223], v[100:101], s[12:13], v[64:65] op_sel_hi:[1,0,1]
	v_cvt_pk_bf16_f32 v64, v76, v77
	v_cvt_pk_bf16_f32 v65, v78, v79
	v_cvt_pk_bf16_f32 v66, v72, v73
	v_cvt_pk_bf16_f32 v67, v74, v75
	v_cvt_pk_bf16_f32 v68, v68, v69
	v_cvt_pk_bf16_f32 v69, v70, v71
	v_cvt_pk_bf16_f32 v70, v222, v223
	v_cvt_pk_bf16_f32 v71, v220, v221
	s_add_u32 s100, s80, 0x18000
	s_addc_u32 s101, s81, 0
	global_store_dwordx4 v144, v[64:67], s[100:101]
	global_store_dwordx4 v144, v[68:71], s[100:101] offset:256
	s_add_u32 s98, s68, 0x58000
	s_addc_u32 s99, s69, 0
	global_load_dwordx4 v[220:223], v144, s[98:99]
	global_load_dwordx4 v[224:227], v144, s[98:99] offset:256
	s_waitcnt vmcnt(12)
	v_lshlrev_b32_e32 v78, 16, v184
	v_and_b32_e32 v79, 0xffff0000, v184
	v_lshlrev_b32_e32 v184, 16, v185
	v_and_b32_e32 v185, 0xffff0000, v185
	v_lshlrev_b32_e32 v80, 16, v186
	v_and_b32_e32 v81, 0xffff0000, v186
	v_lshlrev_b32_e32 v186, 16, v187
	v_and_b32_e32 v187, 0xffff0000, v187
	v_lshlrev_b32_e32 v82, 16, v188
	v_and_b32_e32 v83, 0xffff0000, v188
	v_lshlrev_b32_e32 v188, 16, v189
	v_and_b32_e32 v189, 0xffff0000, v189
	v_lshlrev_b32_e32 v84, 16, v190
	v_and_b32_e32 v85, 0xffff0000, v190
	v_lshlrev_b32_e32 v190, 16, v191
	v_and_b32_e32 v191, 0xffff0000, v191
	v_pk_fma_f32 v[62:63], v[184:185], s[12:13], v[62:63] op_sel_hi:[1,0,1]
	v_pk_fma_f32 v[60:61], v[78:79], s[12:13], v[60:61] op_sel_hi:[1,0,1]
	v_pk_fma_f32 v[58:59], v[186:187], s[12:13], v[58:59] op_sel_hi:[1,0,1]
	v_pk_fma_f32 v[56:57], v[80:81], s[12:13], v[56:57] op_sel_hi:[1,0,1]
	v_pk_fma_f32 v[54:55], v[188:189], s[12:13], v[54:55] op_sel_hi:[1,0,1]
	v_pk_fma_f32 v[52:53], v[82:83], s[12:13], v[52:53] op_sel_hi:[1,0,1]
	v_pk_fma_f32 v[184:185], v[190:191], s[12:13], v[50:51] op_sel_hi:[1,0,1]
	v_pk_fma_f32 v[186:187], v[84:85], s[12:13], v[48:49] op_sel_hi:[1,0,1]
	v_cvt_pk_bf16_f32 v48, v60, v61
	v_cvt_pk_bf16_f32 v49, v62, v63
	v_cvt_pk_bf16_f32 v50, v56, v57
	v_cvt_pk_bf16_f32 v51, v58, v59
	v_cvt_pk_bf16_f32 v52, v52, v53
	v_cvt_pk_bf16_f32 v53, v54, v55
	v_cvt_pk_bf16_f32 v54, v186, v187
	v_cvt_pk_bf16_f32 v55, v184, v185
	s_add_u32 s100, s80, 0x40000
	s_addc_u32 s101, s81, 0
	global_store_dwordx4 v144, v[48:51], s[100:101]
	global_store_dwordx4 v144, v[52:55], s[100:101] offset:256
	s_waitcnt vmcnt(10)
; __device__ __forceinline__ unsigned cvt_pk_bf16(float lo, float hi) { f32x2 v = {lo, hi}; bf16x2v b = __builtin_convertvector(v, bf16x2v); return __builtin_bit_cast(unsigned, b); }
;     __device__ __forceinline__ void operator()(const f32x4 (&acc)[2][2][4][2], const Unit& u, int wr, int wc, int fr, int fq) const {
;         const int row0 = u.pm * BM + wr * 64 + fr; const int col0 = u.pn * BM + wc * 32 + 8 * fq;
; #pragma unroll
;         for (int ai = 0; ai < 2; ++ai)
; #pragma unroll
;             for (int m = 0; m < 4; ++m) { const size_t off = (size_t)(row0 + ai * HALF + m * 16) * ldc + col0;
; #pragma unroll
;                 for (int bj = 0; bj < 2; ++bj) { f32x4 r0, r1;
;                     if (RF32) { r0 = __builtin_nontemporal_load((const f32x4*)((const float*)res + off + bj * HALF)); r1 = __builtin_nontemporal_load((const f32x4*)((const float*)res + off + bj * HALF + 4)); }
;                     else { const u32x4 q = *(const u32x4*)((const bf16_t*)res + off + bj * HALF);
;                         r0 = (f32x4){__builtin_bit_cast(float, q.x << 16), __builtin_bit_cast(float, q.x & 0xffff0000u), __builtin_bit_cast(float, q.y << 16), __builtin_bit_cast(float, q.y & 0xffff0000u)};
;                         r1 = (f32x4){__builtin_bit_cast(float, q.z << 16), __builtin_bit_cast(float, q.z & 0xffff0000u), __builtin_bit_cast(float, q.w << 16), __builtin_bit_cast(float, q.w & 0xffff0000u)}; }
;                     const f32x4 v0 = r0 * alpha + acc[ai][bj][m][0], v1 = r1 * alpha + acc[ai][bj][m][1];
;                     u32x4 w; w.x = cvt_pk_bf16(v0[0], v0[1]); w.y = cvt_pk_bf16(v0[2], v0[3]); w.z = cvt_pk_bf16(v1[0], v1[1]); w.w = cvt_pk_bf16(v1[2], v1[3]);
;                     *(u32x4*)(out + off + bj * HALF) = w; }
;                 if (m & 1) asm volatile("" ::: "memory"); }
;     }
	v_lshlrev_b32_e32 v62, 16, v192
	v_and_b32_e32 v63, 0xffff0000, v192
	v_lshlrev_b32_e32 v192, 16, v193
	v_and_b32_e32 v193, 0xffff0000, v193
	v_lshlrev_b32_e32 v64, 16, v194
	v_and_b32_e32 v65, 0xffff0000, v194
	v_lshlrev_b32_e32 v194, 16, v195
	v_and_b32_e32 v195, 0xffff0000, v195
	v_lshlrev_b32_e32 v66, 16, v208
	v_and_b32_e32 v67, 0xffff0000, v208
	v_lshlrev_b32_e32 v208, 16, v209
	v_and_b32_e32 v209, 0xffff0000, v209
	v_lshlrev_b32_e32 v68, 16, v210
	v_and_b32_e32 v69, 0xffff0000, v210
	v_lshlrev_b32_e32 v210, 16, v211
	v_and_b32_e32 v211, 0xffff0000, v211
	v_pk_fma_f32 v[46:47], v[192:193], s[12:13], v[46:47] op_sel_hi:[1,0,1]
	v_pk_fma_f32 v[44:45], v[62:63], s[12:13], v[44:45] op_sel_hi:[1,0,1]
	v_pk_fma_f32 v[42:43], v[194:195], s[12:13], v[42:43] op_sel_hi:[1,0,1]
	v_pk_fma_f32 v[40:41], v[64:65], s[12:13], v[40:41] op_sel_hi:[1,0,1]
	v_pk_fma_f32 v[38:39], v[208:209], s[12:13], v[38:39] op_sel_hi:[1,0,1]
	v_pk_fma_f32 v[36:37], v[66:67], s[12:13], v[36:37] op_sel_hi:[1,0,1]
	v_pk_fma_f32 v[192:193], v[210:211], s[12:13], v[34:35] op_sel_hi:[1,0,1]
	v_pk_fma_f32 v[194:195], v[68:69], s[12:13], v[32:33] op_sel_hi:[1,0,1]
	v_cvt_pk_bf16_f32 v32, v44, v45
	v_cvt_pk_bf16_f32 v33, v46, v47
	v_cvt_pk_bf16_f32 v34, v40, v41
	v_cvt_pk_bf16_f32 v35, v42, v43
	v_cvt_pk_bf16_f32 v36, v36, v37
	v_cvt_pk_bf16_f32 v37, v38, v39
	v_cvt_pk_bf16_f32 v38, v194, v195
	v_cvt_pk_bf16_f32 v39, v192, v193
	s_add_u32 s100, s80, 0x48000
	s_addc_u32 s101, s81, 0
	global_store_dwordx4 v144, v[32:35], s[100:101]
	global_store_dwordx4 v144, v[36:39], s[100:101] offset:256
	s_waitcnt vmcnt(8)
	v_lshlrev_b32_e32 v46, 16, v212
	v_and_b32_e32 v47, 0xffff0000, v212
	v_lshlrev_b32_e32 v212, 16, v213
	v_and_b32_e32 v213, 0xffff0000, v213
	v_lshlrev_b32_e32 v48, 16, v214
	v_and_b32_e32 v49, 0xffff0000, v214
	v_lshlrev_b32_e32 v214, 16, v215
	v_and_b32_e32 v215, 0xffff0000, v215
	v_lshlrev_b32_e32 v50, 16, v216
	v_and_b32_e32 v51, 0xffff0000, v216
	v_lshlrev_b32_e32 v216, 16, v217
	v_and_b32_e32 v217, 0xffff0000, v217
	v_lshlrev_b32_e32 v52, 16, v218
	v_and_b32_e32 v53, 0xffff0000, v218
	v_lshlrev_b32_e32 v218, 16, v219
	v_and_b32_e32 v219, 0xffff0000, v219
	v_pk_fma_f32 v[30:31], v[212:213], s[12:13], v[30:31] op_sel_hi:[1,0,1]
	v_pk_fma_f32 v[28:29], v[46:47], s[12:13], v[28:29] op_sel_hi:[1,0,1]
	v_pk_fma_f32 v[26:27], v[214:215], s[12:13], v[26:27] op_sel_hi:[1,0,1]
	v_pk_fma_f32 v[24:25], v[48:49], s[12:13], v[24:25] op_sel_hi:[1,0,1]
	v_pk_fma_f32 v[22:23], v[216:217], s[12:13], v[22:23] op_sel_hi:[1,0,1]
	v_pk_fma_f32 v[20:21], v[50:51], s[12:13], v[20:21] op_sel_hi:[1,0,1]
	v_pk_fma_f32 v[212:213], v[218:219], s[12:13], v[18:19] op_sel_hi:[1,0,1]
	v_pk_fma_f32 v[214:215], v[52:53], s[12:13], v[16:17] op_sel_hi:[1,0,1]
	v_cvt_pk_bf16_f32 v16, v28, v29
	v_cvt_pk_bf16_f32 v17, v30, v31
	v_cvt_pk_bf16_f32 v18, v24, v25
	v_cvt_pk_bf16_f32 v19, v26, v27
	v_cvt_pk_bf16_f32 v20, v20, v21
	v_cvt_pk_bf16_f32 v21, v22, v23
	v_cvt_pk_bf16_f32 v22, v214, v215
	v_cvt_pk_bf16_f32 v23, v212, v213
	s_add_u32 s100, s80, 0x50000
	s_addc_u32 s101, s81, 0
	global_store_dwordx4 v144, v[16:19], s[100:101]
	global_store_dwordx4 v144, v[20:23], s[100:101] offset:256
	s_waitcnt vmcnt(6)
	v_lshlrev_b32_e32 v26, 16, v220
	v_and_b32_e32 v27, 0xffff0000, v220
	v_lshlrev_b32_e32 v220, 16, v221
	v_and_b32_e32 v221, 0xffff0000, v221
	v_lshlrev_b32_e32 v28, 16, v222
	v_and_b32_e32 v29, 0xffff0000, v222
	v_lshlrev_b32_e32 v222, 16, v223
	v_and_b32_e32 v223, 0xffff0000, v223
	v_lshlrev_b32_e32 v30, 16, v224
	v_and_b32_e32 v31, 0xffff0000, v224
	v_lshlrev_b32_e32 v224, 16, v225
	v_and_b32_e32 v225, 0xffff0000, v225
	v_lshlrev_b32_e32 v32, 16, v226
	v_and_b32_e32 v33, 0xffff0000, v226
	v_lshlrev_b32_e32 v226, 16, v227
	v_and_b32_e32 v227, 0xffff0000, v227
	v_pk_fma_f32 v[14:15], v[220:221], s[12:13], v[14:15] op_sel_hi:[1,0,1]
	v_pk_fma_f32 v[12:13], v[26:27], s[12:13], v[12:13] op_sel_hi:[1,0,1]
	v_pk_fma_f32 v[10:11], v[222:223], s[12:13], v[10:11] op_sel_hi:[1,0,1]
	v_pk_fma_f32 v[8:9], v[28:29], s[12:13], v[8:9] op_sel_hi:[1,0,1]
	v_pk_fma_f32 v[6:7], v[224:225], s[12:13], v[6:7] op_sel_hi:[1,0,1]
	v_pk_fma_f32 v[4:5], v[30:31], s[12:13], v[4:5] op_sel_hi:[1,0,1]
	v_pk_fma_f32 v[220:221], v[226:227], s[12:13], v[2:3] op_sel_hi:[1,0,1]
	v_pk_fma_f32 v[222:223], v[32:33], s[12:13], v[0:1] op_sel_hi:[1,0,1]
	v_cvt_pk_bf16_f32 v0, v12, v13
	v_cvt_pk_bf16_f32 v1, v14, v15
	v_cvt_pk_bf16_f32 v2, v8, v9
	v_cvt_pk_bf16_f32 v3, v10, v11
	v_cvt_pk_bf16_f32 v4, v4, v5
	v_cvt_pk_bf16_f32 v5, v6, v7
	v_cvt_pk_bf16_f32 v6, v222, v223
	v_cvt_pk_bf16_f32 v7, v220, v221
	s_add_u32 s100, s80, 0x58000
	s_addc_u32 s101, s81, 0
	global_store_dwordx4 v144, v[0:3], s[100:101]
	global_store_dwordx4 v144, v[4:7], s[100:101] offset:256
	s_cbranch_vccnz .LBB0_1695
	s_andn2_b64 vcc, exec, s[6:7]
	s_cbranch_vccnz .LBB0_1694
	s_barrier
	s_branch .LBB0_1694
